# speedup vs baseline: 1.0098x; 1.0019x over previous
; template <bool DIFF>
; __device__ __forceinline__ void attn_item(const Params& p, int l, int I, LAS unsigned char* lds, const int tid) {
;     ...
;     for (int st = 0; st < nt / 2; ++st) {
;         const bool more = (2 * st + 2 < nt);
;         if (more) { gload(2 * st + 2, 0); gload(2 * st + 3, 1); }
;     ...
;         if (more) { lwrite((st + 1) & 1, 0); lwrite((st + 1) & 1, 1); }
;         __syncthreads();
;     }
.LBB0_458:
	s_add_i32 s35, s35, 1
	s_addk_i32 s36, 0x80
	s_add_i32 s37, s37, 2
	s_cmp_eq_u32 s34, s36
	s_waitcnt lgkmcnt(0)
	s_barrier
	s_cbranch_scc1 .LBB0_482

; #define LAS __attribute__((address_space(3)))
; __device__ __forceinline__ s16x4 vtr(const LAS unsigned char* p) { return __builtin_bit_cast(s16x4, __builtin_amdgcn_ds_read_tr16_b64_v4i16((LAS s16x4*)p)); }
; template <bool DIFF>
; __device__ __forceinline__ void attn_item(const Params& p, int l, int I, LAS unsigned char* lds, const int tid) {
;     ...
;         const LAS unsigned char* sbA = lds + (st & 1) * AT_SLOT; const LAS unsigned char* sbB = sbA + AT_SUB;
;         const LAS unsigned char* kbA = sbA + hi * 1024 + r32 * 16; const LAS unsigned char* kbB = sbB + hi * 1024 + r32 * 16;
;         f32x16 a0 = negm1, a1 = negm1, b0 = negm1, b1 = negm1;
;         { bf16x8 kf[6][2];
; #pragma unroll
;           for (int d0 = 0; d0 < 6; ++d0) { kf[d0][0] = *(const LAS bf16x8*)(kbA + d0 * 2048); kf[d0][1] = *(const LAS bf16x8*)(kbA + d0 * 2048 + 512); }
; #pragma unroll
;           for (int d0 = 0; d0 < 6; ++d0) { a0 = __builtin_amdgcn_mfma_f32_32x32x16_bf16(kf[d0][0], qf[d0], a0, 0, 0, 0); a1 = __builtin_amdgcn_mfma_f32_32x32x16_bf16(kf[d0][1], qf[d0], a1, 0, 0, 0); } }
;         { bf16x8 kf[6][2];
; #pragma unroll
;           for (int d0 = 0; d0 < 6; ++d0) { kf[d0][0] = *(const LAS bf16x8*)(kbB + d0 * 2048); kf[d0][1] = *(const LAS bf16x8*)(kbB + d0 * 2048 + 512); }
; #pragma unroll
;           for (int d0 = 0; d0 < 6; ++d0) { b0 = __builtin_amdgcn_mfma_f32_32x32x16_bf16(kf[d0][0], qf[d0], b0, 0, 0, 0); b1 = __builtin_amdgcn_mfma_f32_32x32x16_bf16(kf[d0][1], qf[d0], b1, 0, 0, 0); } }
;         const float m0 = mref1;
;         { bf16x8 vf[2][4]; const LAS unsigned char* vb = sbA + AT_V + vlane;
; #pragma unroll
;           for (int dh = 0; dh < 2; ++dh)
; #pragma unroll
;               for (int k = 0; k < 4; ++k) { const s16x4 lo = vtr(vb + dh * 4096 + k * 1024), hh = vtr(vb + dh * 4096 + k * 1024 + 512);
;                   vf[dh][k] = (bf16x8){lo[0], lo[1], lo[2], lo[3], hh[0], hh[1], hh[2], hh[3]}; }
;           softmax_pv(a0, a1, mref1, negm1, l1, o1, scr, vf, st == 0, r32, hi); }
.LBB0_465:
	s_bitcmp1_b32 s35, 0
	s_cselect_b32 s24, 0xa000, 0
	v_add3_u32 v227, s24, v205, v206
	v_add_u32_e32 v226, s24, v209
	ds_read_b128 v[48:51], v227
	ds_read_b128 v[52:55], v227 offset:2048
	ds_read_b128 v[56:59], v227 offset:4096
	ds_read_b128 v[60:63], v227 offset:6144
	ds_read_b128 v[64:67], v227 offset:8192
	ds_read_b128 v[68:71], v227 offset:10240
	ds_read_b64_tr_b16 v[160:161], v226 offset:12288
	ds_read_b64_tr_b16 v[162:163], v226 offset:12800
	ds_read_b64_tr_b16 v[176:177], v226 offset:16384
	ds_read_b64_tr_b16 v[178:179], v226 offset:16896
	ds_read_b64_tr_b16 v[164:165], v226 offset:13312
	ds_read_b64_tr_b16 v[166:167], v226 offset:13824
	ds_read_b64_tr_b16 v[180:181], v226 offset:17408
	ds_read_b64_tr_b16 v[182:183], v226 offset:17920
	s_waitcnt lgkmcnt(13)
	v_mfma_f32_32x32x16_bf16 v[80:95], v[48:51], v[128:131], v[32:47]
	ds_read_b128 v[48:51], v227 offset:512
	s_waitcnt lgkmcnt(13)
	v_mfma_f32_32x32x16_bf16 v[80:95], v[52:55], v[140:143], v[80:95]
	ds_read_b128 v[52:55], v227 offset:2560
	s_waitcnt lgkmcnt(13)
	v_mfma_f32_32x32x16_bf16 v[80:95], v[56:59], v[144:147], v[80:95]
	ds_read_b128 v[56:59], v227 offset:4608
	s_waitcnt lgkmcnt(13)
	v_mfma_f32_32x32x16_bf16 v[80:95], v[60:63], v[148:151], v[80:95]
	ds_read_b128 v[60:63], v227 offset:6656
	s_waitcnt lgkmcnt(13)
	v_mfma_f32_32x32x16_bf16 v[80:95], v[64:67], v[152:155], v[80:95]
	ds_read_b128 v[64:67], v227 offset:8704
	s_waitcnt lgkmcnt(13)
	v_mfma_f32_32x32x16_bf16 v[80:95], v[68:71], v[156:159], v[80:95]
	ds_read_b128 v[68:71], v227 offset:10752
	s_waitcnt lgkmcnt(5)
	v_mfma_f32_32x32x16_bf16 v[96:111], v[48:51], v[128:131], v[32:47]
	ds_read_b128 v[48:51], v227 offset:20480
	s_waitcnt lgkmcnt(5)
	v_mfma_f32_32x32x16_bf16 v[96:111], v[52:55], v[140:143], v[96:111]
	ds_read_b128 v[52:55], v227 offset:22528
	s_waitcnt lgkmcnt(5)
	v_mfma_f32_32x32x16_bf16 v[96:111], v[56:59], v[144:147], v[96:111]
	ds_read_b128 v[56:59], v227 offset:24576
	s_nop 5
	v_exp_f32_e32 v80, v80
	v_exp_f32_e32 v81, v81
	v_exp_f32_e32 v82, v82
	s_waitcnt lgkmcnt(5)
	v_mfma_f32_32x32x16_bf16 v[96:111], v[60:63], v[148:151], v[96:111]
	ds_read_b128 v[60:63], v227 offset:26624
	v_exp_f32_e32 v83, v83
	v_exp_f32_e32 v84, v84
	v_exp_f32_e32 v85, v85
	v_exp_f32_e32 v86, v86
	s_waitcnt lgkmcnt(5)
	v_mfma_f32_32x32x16_bf16 v[96:111], v[64:67], v[152:155], v[96:111]
	ds_read_b128 v[64:67], v227 offset:28672
	v_exp_f32_e32 v87, v87
	v_cvt_pk_bf16_f32 v72, v80, v81
	v_cvt_pk_bf16_f32 v73, v82, v83
	v_cvt_pk_bf16_f32 v74, v84, v85
	v_cvt_pk_bf16_f32 v75, v86, v87
	v_add_f32_e32 v228, v80, v82
	v_add_f32_e32 v229, v81, v83
	s_waitcnt lgkmcnt(5)
	v_mfma_f32_32x32x16_bf16 v[96:111], v[68:71], v[156:159], v[96:111]
	ds_read_b128 v[68:71], v227 offset:30720
	v_add_f32_e32 v228, v228, v84
	v_add_f32_e32 v229, v229, v85
	v_add_f32_e32 v228, v228, v86
	v_add_f32_e32 v229, v229, v87
	ds_read_b64_tr_b16 v[168:169], v226 offset:14336
	ds_read_b64_tr_b16 v[170:171], v226 offset:14848
	ds_read_b64_tr_b16 v[184:185], v226 offset:18432
	ds_read_b64_tr_b16 v[186:187], v226 offset:18944
	ds_read_b64_tr_b16 v[172:173], v226 offset:15360
	ds_read_b64_tr_b16 v[174:175], v226 offset:15872
	ds_read_b64_tr_b16 v[188:189], v226 offset:19456
	ds_read_b64_tr_b16 v[190:191], v226 offset:19968
	v_exp_f32_e32 v88, v88
	v_exp_f32_e32 v89, v89
	v_exp_f32_e32 v90, v90
	v_exp_f32_e32 v91, v91
	v_mfma_f32_32x32x16_bf16 v[16:31], v[72:75], v[160:163], v[16:31]
	v_exp_f32_e32 v92, v92
	v_exp_f32_e32 v93, v93
	v_exp_f32_e32 v94, v94
	v_exp_f32_e32 v95, v95
	v_cvt_pk_bf16_f32 v76, v88, v89
	v_cvt_pk_bf16_f32 v77, v90, v91
	v_cvt_pk_bf16_f32 v78, v92, v93
	v_cvt_pk_bf16_f32 v79, v94, v95
	v_add_f32_e32 v228, v228, v88
	v_mfma_f32_32x32x16_bf16 v[0:15], v[72:75], v[176:179], v[0:15]
	ds_read_b64_tr_b16 v[160:161], v226 offset:32768
	s_waitcnt lgkmcnt(14)
	ds_read_b64_tr_b16 v[162:163], v226 offset:33280
	s_waitcnt lgkmcnt(14)
	ds_read_b64_tr_b16 v[176:177], v226 offset:36864
	s_waitcnt lgkmcnt(14)
	ds_read_b64_tr_b16 v[178:179], v226 offset:37376
	v_add_f32_e32 v229, v229, v89
	v_add_f32_e32 v228, v228, v90
	v_add_f32_e32 v229, v229, v91
	v_add_f32_e32 v228, v228, v92
	v_add_f32_e32 v229, v229, v93
	v_add_f32_e32 v228, v228, v94
	v_add_f32_e32 v229, v229, v95
	v_exp_f32_e32 v96, v96
	v_exp_f32_e32 v97, v97
	v_mfma_f32_32x32x16_bf16 v[16:31], v[76:79], v[164:167], v[16:31]
	v_exp_f32_e32 v98, v98
	v_exp_f32_e32 v99, v99
	v_exp_f32_e32 v100, v100
	v_mfma_f32_32x32x16_bf16 v[0:15], v[76:79], v[180:183], v[0:15]
	s_waitcnt lgkmcnt(14)
	ds_read_b64_tr_b16 v[164:165], v226 offset:33792
	s_waitcnt lgkmcnt(14)
	ds_read_b64_tr_b16 v[166:167], v226 offset:34304
	s_waitcnt lgkmcnt(14)
	ds_read_b64_tr_b16 v[180:181], v226 offset:37888
	s_waitcnt lgkmcnt(14)
	ds_read_b64_tr_b16 v[182:183], v226 offset:38400
	v_exp_f32_e32 v101, v101
	v_exp_f32_e32 v102, v102
	v_exp_f32_e32 v103, v103
	v_mfma_f32_32x32x16_bf16 v[80:95], v[48:51], v[128:131], v[32:47]
	s_waitcnt lgkmcnt(14)
	ds_read_b128 v[48:51], v227 offset:20992
	v_cvt_pk_bf16_f32 v72, v96, v97
	v_cvt_pk_bf16_f32 v73, v98, v99
	v_cvt_pk_bf16_f32 v74, v100, v101
	v_cvt_pk_bf16_f32 v75, v102, v103
	v_mfma_f32_32x32x16_bf16 v[80:95], v[52:55], v[140:143], v[80:95]
	s_waitcnt lgkmcnt(14)
	ds_read_b128 v[52:55], v227 offset:23040
	v_add_f32_e32 v228, v228, v96
	v_add_f32_e32 v229, v229, v97
	v_add_f32_e32 v228, v228, v98
	v_add_f32_e32 v229, v229, v99
	v_add_f32_e32 v228, v228, v100
	v_add_f32_e32 v229, v229, v101
	v_mfma_f32_32x32x16_bf16 v[80:95], v[56:59], v[144:147], v[80:95]
	s_waitcnt lgkmcnt(14)
; #define LAS __attribute__((address_space(3)))
; __device__ __forceinline__ s16x4 vtr(const LAS unsigned char* p) { return __builtin_bit_cast(s16x4, __builtin_amdgcn_ds_read_tr16_b64_v4i16((LAS s16x4*)p)); }
; template <bool DIFF>
; __device__ __forceinline__ void attn_item(const Params& p, int l, int I, LAS unsigned char* lds, const int tid) {
;     ...
;         { bf16x8 vf[2][4]; const LAS unsigned char* vb = sbA + AT_V + vlane;
; #pragma unroll
;           for (int dh = 0; dh < 2; ++dh)
; #pragma unroll
;               for (int k = 0; k < 4; ++k) { const s16x4 lo = vtr(vb + dh * 4096 + k * 1024), hh = vtr(vb + dh * 4096 + k * 1024 + 512);
;                   vf[dh][k] = (bf16x8){lo[0], lo[1], lo[2], lo[3], hh[0], hh[1], hh[2], hh[3]}; }
;           softmax_pv(a0, a1, mref1, negm1, l1, o1, scr, vf, st == 0, r32, hi); }
;         const float dm = mref1 - m0;
;         if (__builtin_expect(__any(dm != 0.f), 0)) {
; #pragma unroll
;             for (int r = 0; r < 16; ++r) { b0[r] -= dm; b1[r] -= dm; }
;         }
;         { bf16x8 vf[2][4]; const LAS unsigned char* vb = sbB + AT_V + vlane;
; #pragma unroll
;           for (int dh = 0; dh < 2; ++dh)
; #pragma unroll
;               for (int k = 0; k < 4; ++k) { const s16x4 lo = vtr(vb + dh * 4096 + k * 1024), hh = vtr(vb + dh * 4096 + k * 1024 + 512);
;                   vf[dh][k] = (bf16x8){lo[0], lo[1], lo[2], lo[3], hh[0], hh[1], hh[2], hh[3]}; }
;           softmax_pv(b0, b1, mref1, negm1, l1, o1, scr, vf, false, r32, hi); }
;     ...
;         if (more) { lwrite((st + 1) & 1, 0); lwrite((st + 1) & 1, 1); }
;         __syncthreads();
	ds_read_b128 v[56:59], v227 offset:25088
	v_add_f32_e32 v228, v228, v102
	v_add_f32_e32 v229, v229, v103
	v_exp_f32_e32 v104, v104
	v_exp_f32_e32 v105, v105
	v_mfma_f32_32x32x16_bf16 v[80:95], v[60:63], v[148:151], v[80:95]
	s_waitcnt lgkmcnt(14)
	ds_read_b128 v[60:63], v227 offset:27136
	v_exp_f32_e32 v106, v106
	v_exp_f32_e32 v107, v107
	v_exp_f32_e32 v108, v108
	v_mfma_f32_32x32x16_bf16 v[80:95], v[64:67], v[152:155], v[80:95]
	s_waitcnt lgkmcnt(14)
	ds_read_b128 v[64:67], v227 offset:29184
	v_exp_f32_e32 v109, v109
	v_exp_f32_e32 v110, v110
	v_exp_f32_e32 v111, v111
	v_mfma_f32_32x32x16_bf16 v[80:95], v[68:71], v[156:159], v[80:95]
	s_waitcnt lgkmcnt(14)
	ds_read_b128 v[68:71], v227 offset:31232
	v_cvt_pk_bf16_f32 v76, v104, v105
	v_cvt_pk_bf16_f32 v77, v106, v107
	v_cvt_pk_bf16_f32 v78, v108, v109
	v_cvt_pk_bf16_f32 v79, v110, v111
	v_mfma_f32_32x32x16_bf16 v[16:31], v[72:75], v[168:171], v[16:31]
	v_add_f32_e32 v228, v228, v104
	v_add_f32_e32 v229, v229, v105
	v_add_f32_e32 v228, v228, v106
	v_add_f32_e32 v229, v229, v107
	v_add_f32_e32 v228, v228, v108
	v_add_f32_e32 v229, v229, v109
	v_mfma_f32_32x32x16_bf16 v[0:15], v[72:75], v[184:187], v[0:15]
	s_waitcnt lgkmcnt(14)
	ds_read_b64_tr_b16 v[168:169], v226 offset:34816
	s_waitcnt lgkmcnt(14)
	ds_read_b64_tr_b16 v[170:171], v226 offset:35328
	s_waitcnt lgkmcnt(14)
	ds_read_b64_tr_b16 v[184:185], v226 offset:38912
	s_waitcnt lgkmcnt(14)
	ds_read_b64_tr_b16 v[186:187], v226 offset:39424
	v_add_f32_e32 v228, v228, v110
	v_add_f32_e32 v229, v229, v111
	v_add_f32_e32 v228, v228, v229
	v_add_f32_e32 v225, v225, v228
	v_exp_f32_e32 v80, v80
	v_exp_f32_e32 v81, v81
	v_mfma_f32_32x32x16_bf16 v[16:31], v[76:79], v[172:175], v[16:31]
	v_exp_f32_e32 v82, v82
	v_exp_f32_e32 v83, v83
	v_mfma_f32_32x32x16_bf16 v[0:15], v[76:79], v[188:191], v[0:15]
	s_waitcnt lgkmcnt(14)
	ds_read_b64_tr_b16 v[172:173], v226 offset:35840
	s_waitcnt lgkmcnt(14)
	ds_read_b64_tr_b16 v[174:175], v226 offset:36352
	s_waitcnt lgkmcnt(14)
	ds_read_b64_tr_b16 v[188:189], v226 offset:39936
	s_waitcnt lgkmcnt(14)
	ds_read_b64_tr_b16 v[190:191], v226 offset:40448
	v_exp_f32_e32 v84, v84
	v_exp_f32_e32 v85, v85
	v_exp_f32_e32 v86, v86
	s_waitcnt lgkmcnt(13)
	v_mfma_f32_32x32x16_bf16 v[96:111], v[48:51], v[128:131], v[32:47]
	v_exp_f32_e32 v87, v87
	v_cvt_pk_bf16_f32 v72, v80, v81
	v_cvt_pk_bf16_f32 v73, v82, v83
	v_cvt_pk_bf16_f32 v74, v84, v85
	s_waitcnt lgkmcnt(12)
	v_mfma_f32_32x32x16_bf16 v[96:111], v[52:55], v[140:143], v[96:111]
	v_cvt_pk_bf16_f32 v75, v86, v87
	v_add_f32_e32 v228, v80, v82
	v_add_f32_e32 v229, v81, v83
	v_add_f32_e32 v228, v228, v84
	v_add_f32_e32 v229, v229, v85
	s_waitcnt lgkmcnt(11)
	v_mfma_f32_32x32x16_bf16 v[96:111], v[56:59], v[144:147], v[96:111]
	v_add_f32_e32 v228, v228, v86
	v_add_f32_e32 v229, v229, v87
	v_exp_f32_e32 v88, v88
	v_exp_f32_e32 v89, v89
	s_waitcnt lgkmcnt(10)
	v_mfma_f32_32x32x16_bf16 v[96:111], v[60:63], v[148:151], v[96:111]
	v_exp_f32_e32 v90, v90
	v_exp_f32_e32 v91, v91
	v_exp_f32_e32 v92, v92
	s_waitcnt lgkmcnt(9)
	v_mfma_f32_32x32x16_bf16 v[96:111], v[64:67], v[152:155], v[96:111]
	v_exp_f32_e32 v93, v93
	v_exp_f32_e32 v94, v94
	v_exp_f32_e32 v95, v95
	s_waitcnt lgkmcnt(8)
	v_mfma_f32_32x32x16_bf16 v[96:111], v[68:71], v[156:159], v[96:111]
	v_cvt_pk_bf16_f32 v76, v88, v89
	v_cvt_pk_bf16_f32 v77, v90, v91
	v_cvt_pk_bf16_f32 v78, v92, v93
	v_cvt_pk_bf16_f32 v79, v94, v95
	v_mfma_f32_32x32x16_bf16 v[16:31], v[72:75], v[160:163], v[16:31]
	v_add_f32_e32 v228, v228, v88
	v_add_f32_e32 v229, v229, v89
	v_add_f32_e32 v228, v228, v90
	v_add_f32_e32 v229, v229, v91
	v_add_f32_e32 v228, v228, v92
	v_add_f32_e32 v229, v229, v93
	v_mfma_f32_32x32x16_bf16 v[0:15], v[72:75], v[176:179], v[0:15]
	v_add_f32_e32 v228, v228, v94
	v_add_f32_e32 v229, v229, v95
	v_exp_f32_e32 v96, v96
	v_exp_f32_e32 v97, v97
	v_exp_f32_e32 v98, v98
	v_exp_f32_e32 v99, v99
	v_mfma_f32_32x32x16_bf16 v[16:31], v[76:79], v[164:167], v[16:31]
	v_exp_f32_e32 v100, v100
	v_exp_f32_e32 v101, v101
	v_exp_f32_e32 v102, v102
	v_exp_f32_e32 v103, v103
	v_cvt_pk_bf16_f32 v72, v96, v97
	v_cvt_pk_bf16_f32 v73, v98, v99
	v_cvt_pk_bf16_f32 v74, v100, v101
	v_cvt_pk_bf16_f32 v75, v102, v103
	v_add_f32_e32 v228, v228, v96
	v_mfma_f32_32x32x16_bf16 v[0:15], v[76:79], v[180:183], v[0:15]
	v_add_f32_e32 v229, v229, v97
	v_add_f32_e32 v228, v228, v98
	v_add_f32_e32 v229, v229, v99
	v_add_f32_e32 v228, v228, v100
	v_add_f32_e32 v229, v229, v101
	v_add_f32_e32 v228, v228, v102
	v_add_f32_e32 v229, v229, v103
	v_exp_f32_e32 v104, v104
	v_exp_f32_e32 v105, v105
	v_exp_f32_e32 v106, v106
	v_exp_f32_e32 v107, v107
	s_waitcnt lgkmcnt(4)
	v_mfma_f32_32x32x16_bf16 v[16:31], v[72:75], v[168:171], v[16:31]
	v_exp_f32_e32 v108, v108
	v_exp_f32_e32 v109, v109
	v_exp_f32_e32 v110, v110
	v_exp_f32_e32 v111, v111
	v_cvt_pk_bf16_f32 v76, v104, v105
	v_cvt_pk_bf16_f32 v77, v106, v107
	v_cvt_pk_bf16_f32 v78, v108, v109
	v_cvt_pk_bf16_f32 v79, v110, v111
	v_add_f32_e32 v228, v228, v104
	v_mfma_f32_32x32x16_bf16 v[0:15], v[72:75], v[184:187], v[0:15]
	v_add_f32_e32 v229, v229, v105
	v_add_f32_e32 v228, v228, v106
	v_add_f32_e32 v229, v229, v107
	v_add_f32_e32 v228, v228, v108
	v_add_f32_e32 v229, v229, v109
	v_add_f32_e32 v228, v228, v110
	v_add_f32_e32 v229, v229, v111
	s_waitcnt lgkmcnt(0)
	v_mfma_f32_32x32x16_bf16 v[16:31], v[76:79], v[172:175], v[16:31]
	v_mfma_f32_32x32x16_bf16 v[0:15], v[76:79], v[188:191], v[0:15]
	v_add_f32_e32 v228, v228, v229
	v_add_f32_e32 v225, v225, v228
	v_cmp_lt_f32_e32 vcc, 0x47800000, v225
	s_cbranch_vccnz .Lmp
.Lmpc:
	s_andn2_b64 vcc, exec, s[22:23]
	s_cbranch_vccnz .LBB0_458
	s_andn2_b32 s22, 1, s35
	s_mul_i32 s22, s22, 0xa000
	s_add_i32 s24, s22, 0
	v_add_u32_e32 v80, s24, v204
	v_add_u32_e32 v81, s24, v203
	s_waitcnt vmcnt(3)
	ds_write_b128 v80, v[120:123]
	s_waitcnt vmcnt(2)
	ds_write_b128 v81, v[124:127] offset:12288
	s_and_saveexec_b64 s[22:23], s[4:5]
	s_xor_b64 s[22:23], exec, s[22:23]
	s_cbranch_execz .LBB0_473
	s_waitcnt vmcnt(1)
	ds_write_b128 v80, v[132:135] offset:20480
	s_waitcnt vmcnt(0)
	ds_write_b128 v81, v[136:139] offset:32768

; __device__ __forceinline__ int crow(int r, int hi) { return (r & 3) + 8 * (r >> 2) + 4 * hi; }
; __device__ __forceinline__ void softmax_pv(f32x16& s0, f32x16& s1, float& mref, f32x16& negm, float& lsum, f32x16 (&o)[2], LAS float* fac, const bf16x8 (&vf)[2][4], bool first, int r32, int hi) {
;     ...
;     if (__builtin_expect(first || __any(mx > 16.0f), 0)) {
;         const float d = first ? mx : fmaxf(mx, 0.f);
;         const float f = __builtin_amdgcn_exp2f(-d);
;         lsum *= f; mref += d;
; #pragma unroll
;         for (int r = 0; r < 16; ++r) { s0[r] -= d; s1[r] -= d; negm[r] = -mref; }
;         if (hi == 0) fac[r32] = f;
;         asm volatile("s_waitcnt lgkmcnt(0)" ::: "memory");
; #pragma unroll
;         for (int r = 0; r < 16; ++r) { const float ff = fac[crow(r, hi)]; o[0][r] *= ff; o[1][r] *= ff; }
;     }
.Lmp:
	v_mov_b32_e32 v230, v225
	v_mov_b32_e32 v231, v225
	s_nop 1
	v_permlane32_swap_b32_e32 v230, v231
	v_add_f32_e32 v230, v230, v231
	v_log_f32_e32 v218, v230
	s_nop 0
	v_ceil_f32_e32 v218, v218
	v_max_f32_e32 v218, 0, v218
	v_exp_f32_e64 v219, -v218
	s_nop 7
	s_and_saveexec_b64 s[24:25], s[8:9]
	ds_write_b32 v208, v219
	s_or_b64 exec, exec, s[24:25]
	v_add_f32_e32 v211, v211, v218
	v_mul_f32_e32 v225, v225, v219
	v_xor_b32_e32 v32, 0x80000000, v211
	v_mov_b32_e32 v33, v32
	v_mov_b32_e32 v34, v32
	v_mov_b32_e32 v35, v32
	v_mov_b32_e32 v36, v32
	v_mov_b32_e32 v37, v32
	v_mov_b32_e32 v38, v32
	v_mov_b32_e32 v39, v32
	v_mov_b32_e32 v40, v32
	v_mov_b32_e32 v41, v32
	v_mov_b32_e32 v42, v32
	v_mov_b32_e32 v43, v32
	v_mov_b32_e32 v44, v32
	v_mov_b32_e32 v45, v32
	v_mov_b32_e32 v46, v32
	v_mov_b32_e32 v47, v32
	s_waitcnt lgkmcnt(0)
	ds_read_b128 v[72:75], v210
	ds_read_b128 v[76:79], v210 offset:32
	s_waitcnt lgkmcnt(0)
	v_pk_mul_f32 v[16:17], v[16:17], v[72:73]
	v_pk_mul_f32 v[18:19], v[18:19], v[74:75]
	v_pk_mul_f32 v[20:21], v[20:21], v[76:77]
	v_pk_mul_f32 v[22:23], v[22:23], v[78:79]
	v_pk_mul_f32 v[0:1], v[0:1], v[72:73]
	v_pk_mul_f32 v[2:3], v[2:3], v[74:75]
	v_pk_mul_f32 v[4:5], v[4:5], v[76:77]
	v_pk_mul_f32 v[6:7], v[6:7], v[78:79]
	ds_read_b128 v[72:75], v210 offset:64
	ds_read_b128 v[76:79], v210 offset:96
	s_waitcnt lgkmcnt(0)
	v_pk_mul_f32 v[24:25], v[24:25], v[72:73]
	v_pk_mul_f32 v[26:27], v[26:27], v[74:75]
	v_pk_mul_f32 v[28:29], v[28:29], v[76:77]
	v_pk_mul_f32 v[30:31], v[30:31], v[78:79]
	v_pk_mul_f32 v[8:9], v[8:9], v[72:73]
	v_pk_mul_f32 v[10:11], v[10:11], v[74:75]
	v_pk_mul_f32 v[12:13], v[12:13], v[76:77]
	v_pk_mul_f32 v[14:15], v[14:15], v[78:79]
	s_branch .Lmpc
